# fp6 unit epilogue (sigmoid): v_pk_mul_f32 / v_pk_add_f32 for the scale and +1 (24 instead of 32 VALU per block, bit-identical)
# speedup vs baseline: 1.0046x; 1.0046x over previous
.LBB0_171:
	v_and_b32_e32 v3, 48, v0
	v_lshrrev_b32_e32 v2, 4, v178
	v_lshl_or_b32 v3, v193, 6, v3
	v_lshlrev_b32_e32 v4, 3, v193
	s_lshl_b32 s2, s10, 12
	v_lshl_or_b32 v4, v2, 7, v4
	v_bitop3_b32 v5, s2, v3, v1 bitop3:0xf6
	s_lshl_b32 s2, s12, 11
	v_bitop3_b32 v194, s2, v3, v1 bitop3:0xf6
	v_or_b32_e32 v3, s11, v4
	s_lshl_b32 s2, s12, 5
	s_waitcnt vmcnt(4)
	v_or_b32_e32 v195, 0x2000, v3
	v_lshl_or_b32 v3, s10, 11, v4
	s_add_i32 s43, s11, 0
	v_lshl_or_b32 v2, v2, 3, s2
	v_mov_b32_e32 v50, 0
	s_mov_b32 s70, 0
	s_add_i32 s44, s43, 0xe000
	s_add_i32 s45, s43, 0x10000
	s_add_i32 s46, s43, 0x12000
	s_add_i32 s47, s43, 0x14000
	s_add_i32 s48, s43, 0x16000
	s_add_i32 s49, s43, 0x2000
	s_add_i32 s50, s43, 0x6000
	s_add_i32 s51, s43, 0x18000
	s_add_i32 s52, s43, 0x1a000
	s_add_i32 s53, s43, 0x1c000
	s_add_i32 s54, s43, 0x1e000
	s_add_i32 s55, s43, 0xa000
	s_add_i32 s56, s43, 0xd000
	s_add_i32 s57, s43, 0x11000
	s_add_i32 s58, s43, 0x15000
	s_add_i32 s59, s43, 0x1000
	s_add_i32 s60, s43, 0x5000
	s_add_i32 s61, s43, 0x19000
	s_add_i32 s62, s43, 0x1d000
	s_add_i32 s63, s43, 0x9000
	v_or_b32_e32 v196, 0x1400, v2
	s_add_i32 s64, s43, 0xc000
	s_add_i32 s65, s43, 0x4000
	s_add_i32 s66, s43, 0x8000
	s_mov_b32 s24, 0x3b800000
	s_mov_b32 s67, 0xcc00
	v_add_u32_e32 v197, 0, v5
	v_add_u32_e32 v198, 0, v3
	v_mov_b32_e32 v51, v50
	v_mov_b32_e32 v52, v50
	v_mov_b32_e32 v53, v50
	v_mov_b32_e32 v54, v50
	v_mov_b32_e32 v55, v50
	v_mov_b32_e32 v56, v50
	v_mov_b32_e32 v57, v50
	v_mov_b32_e32 v58, v50
	v_mov_b32_e32 v59, v50
	v_mov_b32_e32 v60, v50
	v_mov_b32_e32 v61, v50
	v_mov_b32_e32 v62, v50
	v_mov_b32_e32 v63, v50
	v_mov_b32_e32 v64, v50
	v_mov_b32_e32 v65, v50
	v_mov_b32_e32 v66, v50
	v_mov_b32_e32 v67, v50
	v_mov_b32_e32 v68, v50
	v_mov_b32_e32 v69, v50
	v_mov_b32_e32 v70, v50
	v_mov_b32_e32 v71, v50
	v_mov_b32_e32 v72, v50
	v_mov_b32_e32 v73, v50
	v_mov_b32_e32 v74, v50
	v_mov_b32_e32 v75, v50
	v_mov_b32_e32 v76, v50
	v_mov_b32_e32 v77, v50
	v_mov_b32_e32 v78, v50
	v_mov_b32_e32 v79, v50
	v_mov_b32_e32 v80, v50
	v_mov_b32_e32 v81, v50
	v_mov_b32_e32 v82, v50
	v_mov_b32_e32 v83, v50
	v_mov_b32_e32 v84, v50
	v_mov_b32_e32 v85, v50
	v_mov_b32_e32 v86, v50
	v_mov_b32_e32 v87, v50
	v_mov_b32_e32 v88, v50
	v_mov_b32_e32 v89, v50
	v_mov_b32_e32 v90, v50
	v_mov_b32_e32 v91, v50
	v_mov_b32_e32 v92, v50
	v_mov_b32_e32 v93, v50
	v_mov_b32_e32 v94, v50
	v_mov_b32_e32 v95, v50
	v_mov_b32_e32 v96, v50
	v_mov_b32_e32 v97, v50
	v_mov_b32_e32 v98, v50
	v_mov_b32_e32 v99, v50
	v_mov_b32_e32 v100, v50
	v_mov_b32_e32 v101, v50
	v_mov_b32_e32 v102, v50
	v_mov_b32_e32 v103, v50
	v_mov_b32_e32 v104, v50
	v_mov_b32_e32 v105, v50
	v_mov_b32_e32 v106, v50
	v_mov_b32_e32 v107, v50
	v_mov_b32_e32 v108, v50
	v_mov_b32_e32 v109, v50
	v_mov_b32_e32 v110, v50
	v_mov_b32_e32 v111, v50
	v_mov_b32_e32 v112, v50
	v_mov_b32_e32 v113, v50
	v_mov_b32_e32 v114, v50
	v_mov_b32_e32 v115, v50
	v_mov_b32_e32 v116, v50
	v_mov_b32_e32 v117, v50
	v_mov_b32_e32 v118, v50
	v_mov_b32_e32 v119, v50
	v_mov_b32_e32 v120, v50
	v_mov_b32_e32 v121, v50
	v_mov_b32_e32 v122, v50
	v_mov_b32_e32 v123, v50
	v_mov_b32_e32 v124, v50
	v_mov_b32_e32 v125, v50
	v_mov_b32_e32 v126, v50
	v_mov_b32_e32 v127, v50
	v_mov_b32_e32 v128, v50
	v_mov_b32_e32 v129, v50
	v_mov_b32_e32 v130, v50
	v_mov_b32_e32 v131, v50
	v_mov_b32_e32 v132, v50
	v_mov_b32_e32 v133, v50
	v_mov_b32_e32 v134, v50
	v_mov_b32_e32 v135, v50
	v_mov_b32_e32 v136, v50
	v_mov_b32_e32 v137, v50
	v_mov_b32_e32 v138, v50
	v_mov_b32_e32 v139, v50
	v_mov_b32_e32 v140, v50
	v_mov_b32_e32 v141, v50
	v_mov_b32_e32 v142, v50
	v_mov_b32_e32 v143, v50
	v_mov_b32_e32 v144, v50
	v_mov_b32_e32 v145, v50
	v_mov_b32_e32 v146, v50
	v_mov_b32_e32 v147, v50
	v_mov_b32_e32 v148, v50
	v_mov_b32_e32 v149, v50
	v_mov_b32_e32 v150, v50
	v_mov_b32_e32 v151, v50
	v_mov_b32_e32 v152, v50
	v_mov_b32_e32 v153, v50
	v_mov_b32_e32 v154, v50
	v_mov_b32_e32 v155, v50
	v_mov_b32_e32 v156, v50
	v_mov_b32_e32 v157, v50
	v_mov_b32_e32 v158, v50
	v_mov_b32_e32 v159, v50
	v_mov_b32_e32 v160, v50
	v_mov_b32_e32 v161, v50
	v_mov_b32_e32 v162, v50
	v_mov_b32_e32 v163, v50
	v_mov_b32_e32 v164, v50
	v_mov_b32_e32 v165, v50
	v_mov_b32_e32 v166, v50
	v_mov_b32_e32 v167, v50
	v_mov_b32_e32 v168, v50
	v_mov_b32_e32 v169, v50
	v_mov_b32_e32 v170, v50
	v_mov_b32_e32 v171, v50
	v_mov_b32_e32 v172, v50
	v_mov_b32_e32 v173, v50
	v_mov_b32_e32 v174, v50
	v_mov_b32_e32 v175, v50
	v_mov_b32_e32 v176, v50
	v_mov_b32_e32 v177, v50
	v_lshl_or_b32 v199, s10, 6, v193
	v_mov_b32_e32 v200, 0x7f7f7f7f
	v_mov_b64_e32 v[186:187], 0xa20
	v_mov_b64_e32 v[188:189], 0xa1f
	s_barrier
	s_mov_b32 s32, 1
	s_mov_b32 s84, 0
	v_mov_b32_e32 v244, v180
	v_mov_b32_e32 v245, v182
	v_mov_b32_e32 v246, v184
	s_mov_b32 s88, 0xbbb8aa3b
	s_mov_b32 s89, 0xbbb8aa3b
	s_mov_b32 s90, 1.0
	s_mov_b32 s91, 1.0
	s_branch .LBB0_174

.LBB0_200:
	s_add_i32 s2, s37, -5
	s_cmp_lt_u32 s2, 4
	s_cselect_b64 s[2:3], -1, 0
	s_cmp_gt_i32 s37, 12
	s_cselect_b64 s[28:29], -1, 0
	s_or_b64 s[2:3], s[28:29], s[2:3]
	v_cndmask_b32_e64 v2, 0, 1, s[2:3]
	s_cmp_lt_i32 s37, 17
	v_readfirstlane_b32 s2, v2
	s_cselect_b32 s28, s2, 2
	s_cmp_gt_i32 s28, 1
	s_mov_b64 s[2:3], -1
	s_cbranch_scc0 .LBB0_202
	s_nop 1
	v_pk_mul_f32 v[8:9], v[170:171], s[88:89]
	v_pk_mul_f32 v[12:13], v[172:173], s[88:89]
	v_pk_mul_f32 v[6:7], v[174:175], s[88:89]
	v_pk_mul_f32 v[10:11], v[176:177], s[88:89]
	v_exp_f32_e32 v8, v8
	v_exp_f32_e32 v9, v9
	v_exp_f32_e32 v12, v12
	v_exp_f32_e32 v13, v13
	v_exp_f32_e32 v6, v6
	v_exp_f32_e32 v7, v7
	v_exp_f32_e32 v10, v10
	v_exp_f32_e32 v11, v11
	v_pk_add_f32 v[8:9], v[8:9], s[90:91]
	v_pk_add_f32 v[12:13], v[12:13], s[90:91]
	v_pk_add_f32 v[6:7], v[6:7], s[90:91]
	v_pk_add_f32 v[10:11], v[10:11], s[90:91]
	v_rcp_f32_e32 v8, v8
	v_rcp_f32_e32 v9, v9
	v_rcp_f32_e32 v12, v12
	v_rcp_f32_e32 v13, v13
	v_rcp_f32_e32 v6, v6
	v_rcp_f32_e32 v7, v7
	v_rcp_f32_e32 v10, v10
	v_rcp_f32_e32 v11, v11
	s_mov_b64 s[2:3], 0

.LBB0_207:
	v_lshl_add_u32 v14, s38, 8, v199
	v_lshl_add_u32 v2, s37, 8, v196
	v_mov_b64_e32 v[4:5], s[16:17]
	v_ashrrev_i32_e32 v3, 31, v2
	v_mad_i64_i32 v[4:5], s[2:3], v14, s67, v[4:5]
	v_lshl_add_u64 v[4:5], v[2:3], 1, v[4:5]
	v_cvt_pk_bf16_f32 v6, v6, v7
	v_cvt_pk_bf16_f32 v7, v10, v11
	v_cvt_pk_bf16_f32 v8, v8, v9
	v_cvt_pk_bf16_f32 v9, v12, v13
	s_cmp_gt_i32 s28, 1
	s_mov_b64 s[2:3], -1
	global_store_dwordx4 v[4:5], v[6:9], off
	s_cbranch_scc0 .LBB0_209
	s_nop 0
	s_nop 1
	v_pk_mul_f32 v[8:9], v[138:139], s[88:89]
	v_pk_mul_f32 v[12:13], v[140:141], s[88:89]
	v_pk_mul_f32 v[6:7], v[142:143], s[88:89]
	v_pk_mul_f32 v[10:11], v[144:145], s[88:89]
	v_exp_f32_e32 v8, v8
	v_exp_f32_e32 v9, v9
	v_exp_f32_e32 v12, v12
	v_exp_f32_e32 v13, v13
	v_exp_f32_e32 v6, v6
	v_exp_f32_e32 v7, v7
	v_exp_f32_e32 v10, v10
	v_exp_f32_e32 v11, v11
	v_pk_add_f32 v[8:9], v[8:9], s[90:91]
	v_pk_add_f32 v[12:13], v[12:13], s[90:91]
	v_pk_add_f32 v[6:7], v[6:7], s[90:91]
	v_pk_add_f32 v[10:11], v[10:11], s[90:91]
	v_rcp_f32_e32 v8, v8
	v_rcp_f32_e32 v9, v9
	v_rcp_f32_e32 v12, v12
	v_rcp_f32_e32 v13, v13
	v_rcp_f32_e32 v6, v6
	v_rcp_f32_e32 v7, v7
	v_rcp_f32_e32 v10, v10
	v_rcp_f32_e32 v11, v11
	s_mov_b64 s[2:3], 0

.LBB0_214:
	v_cvt_pk_bf16_f32 v6, v6, v7
	v_cvt_pk_bf16_f32 v7, v10, v11
	v_cvt_pk_bf16_f32 v8, v8, v9
	v_cvt_pk_bf16_f32 v9, v12, v13
	s_cmp_gt_i32 s28, 1
	s_mov_b64 s[2:3], -1
	global_store_dwordx4 v[4:5], v[6:9], off offset:256
	s_cbranch_scc0 .LBB0_216
	s_nop 1
	v_pk_mul_f32 v[8:9], v[162:163], s[88:89]
	v_pk_mul_f32 v[12:13], v[164:165], s[88:89]
	v_pk_mul_f32 v[6:7], v[166:167], s[88:89]
	v_pk_mul_f32 v[10:11], v[168:169], s[88:89]
	v_exp_f32_e32 v8, v8
	v_exp_f32_e32 v9, v9
	v_exp_f32_e32 v12, v12
	v_exp_f32_e32 v13, v13
	v_exp_f32_e32 v6, v6
	v_exp_f32_e32 v7, v7
	v_exp_f32_e32 v10, v10
	v_exp_f32_e32 v11, v11
	v_pk_add_f32 v[8:9], v[8:9], s[90:91]
	v_pk_add_f32 v[12:13], v[12:13], s[90:91]
	v_pk_add_f32 v[6:7], v[6:7], s[90:91]
	v_pk_add_f32 v[10:11], v[10:11], s[90:91]
	v_rcp_f32_e32 v8, v8
	v_rcp_f32_e32 v9, v9
	v_rcp_f32_e32 v12, v12
	v_rcp_f32_e32 v13, v13
	v_rcp_f32_e32 v6, v6
	v_rcp_f32_e32 v7, v7
	v_rcp_f32_e32 v10, v10
	v_rcp_f32_e32 v11, v11
	s_mov_b64 s[2:3], 0

.LBB0_221:
	v_or_b32_e32 v15, 16, v14
	v_mov_b64_e32 v[4:5], s[16:17]
	v_mad_i64_i32 v[4:5], s[2:3], v15, s67, v[4:5]
	v_lshl_add_u64 v[4:5], v[2:3], 1, v[4:5]
	v_cvt_pk_bf16_f32 v6, v6, v7
	v_cvt_pk_bf16_f32 v7, v10, v11
	v_cvt_pk_bf16_f32 v8, v8, v9
	v_cvt_pk_bf16_f32 v9, v12, v13
	s_cmp_gt_i32 s28, 1
	s_mov_b64 s[2:3], -1
	global_store_dwordx4 v[4:5], v[6:9], off
	s_cbranch_scc0 .LBB0_223
	s_nop 0
	s_nop 1
	v_pk_mul_f32 v[8:9], v[130:131], s[88:89]
	v_pk_mul_f32 v[12:13], v[132:133], s[88:89]
	v_pk_mul_f32 v[6:7], v[134:135], s[88:89]
	v_pk_mul_f32 v[10:11], v[136:137], s[88:89]
	v_exp_f32_e32 v8, v8
	v_exp_f32_e32 v9, v9
	v_exp_f32_e32 v12, v12
	v_exp_f32_e32 v13, v13
	v_exp_f32_e32 v6, v6
	v_exp_f32_e32 v7, v7
	v_exp_f32_e32 v10, v10
	v_exp_f32_e32 v11, v11
	v_pk_add_f32 v[8:9], v[8:9], s[90:91]
	v_pk_add_f32 v[12:13], v[12:13], s[90:91]
	v_pk_add_f32 v[6:7], v[6:7], s[90:91]
	v_pk_add_f32 v[10:11], v[10:11], s[90:91]
	v_rcp_f32_e32 v8, v8
	v_rcp_f32_e32 v9, v9
	v_rcp_f32_e32 v12, v12
	v_rcp_f32_e32 v13, v13
	v_rcp_f32_e32 v6, v6
	v_rcp_f32_e32 v7, v7
	v_rcp_f32_e32 v10, v10
	v_rcp_f32_e32 v11, v11
	s_mov_b64 s[2:3], 0

.LBB0_228:
	v_cvt_pk_bf16_f32 v6, v6, v7
	v_cvt_pk_bf16_f32 v7, v10, v11
	v_cvt_pk_bf16_f32 v8, v8, v9
	v_cvt_pk_bf16_f32 v9, v12, v13
	s_cmp_gt_i32 s28, 1
	s_mov_b64 s[2:3], -1
	global_store_dwordx4 v[4:5], v[6:9], off offset:256
	s_cbranch_scc0 .LBB0_230
	s_nop 1
	v_pk_mul_f32 v[8:9], v[154:155], s[88:89]
	v_pk_mul_f32 v[12:13], v[156:157], s[88:89]
	v_pk_mul_f32 v[6:7], v[158:159], s[88:89]
	v_pk_mul_f32 v[10:11], v[160:161], s[88:89]
	v_exp_f32_e32 v8, v8
	v_exp_f32_e32 v9, v9
	v_exp_f32_e32 v12, v12
	v_exp_f32_e32 v13, v13
	v_exp_f32_e32 v6, v6
	v_exp_f32_e32 v7, v7
	v_exp_f32_e32 v10, v10
	v_exp_f32_e32 v11, v11
	v_pk_add_f32 v[8:9], v[8:9], s[90:91]
	v_pk_add_f32 v[12:13], v[12:13], s[90:91]
	v_pk_add_f32 v[6:7], v[6:7], s[90:91]
	v_pk_add_f32 v[10:11], v[10:11], s[90:91]
	v_rcp_f32_e32 v8, v8
	v_rcp_f32_e32 v9, v9
	v_rcp_f32_e32 v12, v12
	v_rcp_f32_e32 v13, v13
	v_rcp_f32_e32 v6, v6
	v_rcp_f32_e32 v7, v7
	v_rcp_f32_e32 v10, v10
	v_rcp_f32_e32 v11, v11
	s_mov_b64 s[2:3], 0

.LBB0_235:
	v_or_b32_e32 v15, 32, v14
	v_mov_b64_e32 v[4:5], s[16:17]
	v_mad_i64_i32 v[4:5], s[2:3], v15, s67, v[4:5]
	v_lshl_add_u64 v[4:5], v[2:3], 1, v[4:5]
	v_cvt_pk_bf16_f32 v6, v6, v7
	v_cvt_pk_bf16_f32 v7, v10, v11
	v_cvt_pk_bf16_f32 v8, v8, v9
	v_cvt_pk_bf16_f32 v9, v12, v13
	s_cmp_gt_i32 s28, 1
	s_mov_b64 s[2:3], -1
	global_store_dwordx4 v[4:5], v[6:9], off
	s_cbranch_scc0 .LBB0_237
	s_nop 0
	s_nop 1
	v_pk_mul_f32 v[8:9], v[122:123], s[88:89]
	v_pk_mul_f32 v[12:13], v[124:125], s[88:89]
	v_pk_mul_f32 v[6:7], v[126:127], s[88:89]
	v_pk_mul_f32 v[10:11], v[128:129], s[88:89]
	v_exp_f32_e32 v8, v8
	v_exp_f32_e32 v9, v9
	v_exp_f32_e32 v12, v12
	v_exp_f32_e32 v13, v13
	v_exp_f32_e32 v6, v6
	v_exp_f32_e32 v7, v7
	v_exp_f32_e32 v10, v10
	v_exp_f32_e32 v11, v11
	v_pk_add_f32 v[8:9], v[8:9], s[90:91]
	v_pk_add_f32 v[12:13], v[12:13], s[90:91]
	v_pk_add_f32 v[6:7], v[6:7], s[90:91]
	v_pk_add_f32 v[10:11], v[10:11], s[90:91]
	v_rcp_f32_e32 v8, v8
	v_rcp_f32_e32 v9, v9
	v_rcp_f32_e32 v12, v12
	v_rcp_f32_e32 v13, v13
	v_rcp_f32_e32 v6, v6
	v_rcp_f32_e32 v7, v7
	v_rcp_f32_e32 v10, v10
	v_rcp_f32_e32 v11, v11
	s_mov_b64 s[2:3], 0

.LBB0_242:
	v_cvt_pk_bf16_f32 v6, v6, v7
	v_cvt_pk_bf16_f32 v7, v10, v11
	v_cvt_pk_bf16_f32 v8, v8, v9
	v_cvt_pk_bf16_f32 v9, v12, v13
	s_cmp_gt_i32 s28, 1
	s_mov_b64 s[2:3], -1
	global_store_dwordx4 v[4:5], v[6:9], off offset:256
	s_cbranch_scc0 .LBB0_244
	s_nop 1
	v_pk_mul_f32 v[8:9], v[146:147], s[88:89]
	v_pk_mul_f32 v[12:13], v[148:149], s[88:89]
	v_pk_mul_f32 v[6:7], v[150:151], s[88:89]
	v_pk_mul_f32 v[10:11], v[152:153], s[88:89]
	v_exp_f32_e32 v8, v8
	v_exp_f32_e32 v9, v9
	v_exp_f32_e32 v12, v12
	v_exp_f32_e32 v13, v13
	v_exp_f32_e32 v6, v6
	v_exp_f32_e32 v7, v7
	v_exp_f32_e32 v10, v10
	v_exp_f32_e32 v11, v11
	v_pk_add_f32 v[8:9], v[8:9], s[90:91]
	v_pk_add_f32 v[12:13], v[12:13], s[90:91]
	v_pk_add_f32 v[6:7], v[6:7], s[90:91]
	v_pk_add_f32 v[10:11], v[10:11], s[90:91]
	v_rcp_f32_e32 v8, v8
	v_rcp_f32_e32 v9, v9
	v_rcp_f32_e32 v12, v12
	v_rcp_f32_e32 v13, v13
	v_rcp_f32_e32 v6, v6
	v_rcp_f32_e32 v7, v7
	v_rcp_f32_e32 v10, v10
	v_rcp_f32_e32 v11, v11
	s_mov_b64 s[2:3], 0

.LBB0_249:
	v_or_b32_e32 v15, 48, v14
	v_mov_b64_e32 v[4:5], s[16:17]
	v_mad_i64_i32 v[4:5], s[2:3], v15, s67, v[4:5]
	v_lshl_add_u64 v[4:5], v[2:3], 1, v[4:5]
	v_cvt_pk_bf16_f32 v6, v6, v7
	v_cvt_pk_bf16_f32 v7, v10, v11
	v_cvt_pk_bf16_f32 v8, v8, v9
	v_cvt_pk_bf16_f32 v9, v12, v13
	s_cmp_gt_i32 s28, 1
	s_mov_b64 s[2:3], -1
	global_store_dwordx4 v[4:5], v[6:9], off
	s_cbranch_scc0 .LBB0_251
	s_nop 0
	s_nop 1
	v_pk_mul_f32 v[8:9], v[114:115], s[88:89]
	v_pk_mul_f32 v[12:13], v[116:117], s[88:89]
	v_pk_mul_f32 v[6:7], v[118:119], s[88:89]
	v_pk_mul_f32 v[10:11], v[120:121], s[88:89]
	v_exp_f32_e32 v8, v8
	v_exp_f32_e32 v9, v9
	v_exp_f32_e32 v12, v12
	v_exp_f32_e32 v13, v13
	v_exp_f32_e32 v6, v6
	v_exp_f32_e32 v7, v7
	v_exp_f32_e32 v10, v10
	v_exp_f32_e32 v11, v11
	v_pk_add_f32 v[8:9], v[8:9], s[90:91]
	v_pk_add_f32 v[12:13], v[12:13], s[90:91]
	v_pk_add_f32 v[6:7], v[6:7], s[90:91]
	v_pk_add_f32 v[10:11], v[10:11], s[90:91]
	v_rcp_f32_e32 v8, v8
	v_rcp_f32_e32 v9, v9
	v_rcp_f32_e32 v12, v12
	v_rcp_f32_e32 v13, v13
	v_rcp_f32_e32 v6, v6
	v_rcp_f32_e32 v7, v7
	v_rcp_f32_e32 v10, v10
	v_rcp_f32_e32 v11, v11
	s_mov_b64 s[2:3], 0

.LBB0_256:
	v_cvt_pk_bf16_f32 v6, v6, v7
	v_cvt_pk_bf16_f32 v7, v10, v11
	v_cvt_pk_bf16_f32 v8, v8, v9
	v_cvt_pk_bf16_f32 v9, v12, v13
	s_cmp_gt_i32 s28, 1
	s_mov_b64 s[2:3], -1
	global_store_dwordx4 v[4:5], v[6:9], off offset:256
	s_cbranch_scc0 .LBB0_258
	s_nop 1
	v_pk_mul_f32 v[8:9], v[106:107], s[88:89]
	v_pk_mul_f32 v[12:13], v[108:109], s[88:89]
	v_pk_mul_f32 v[6:7], v[110:111], s[88:89]
	v_pk_mul_f32 v[10:11], v[112:113], s[88:89]
	v_exp_f32_e32 v8, v8
	v_exp_f32_e32 v9, v9
	v_exp_f32_e32 v12, v12
	v_exp_f32_e32 v13, v13
	v_exp_f32_e32 v6, v6
	v_exp_f32_e32 v7, v7
	v_exp_f32_e32 v10, v10
	v_exp_f32_e32 v11, v11
	v_pk_add_f32 v[8:9], v[8:9], s[90:91]
	v_pk_add_f32 v[12:13], v[12:13], s[90:91]
	v_pk_add_f32 v[6:7], v[6:7], s[90:91]
	v_pk_add_f32 v[10:11], v[10:11], s[90:91]
	v_rcp_f32_e32 v8, v8
	v_rcp_f32_e32 v9, v9
	v_rcp_f32_e32 v12, v12
	v_rcp_f32_e32 v13, v13
	v_rcp_f32_e32 v6, v6
	v_rcp_f32_e32 v7, v7
	v_rcp_f32_e32 v10, v10
	v_rcp_f32_e32 v11, v11
	s_mov_b64 s[2:3], 0

.LBB0_263:
	v_add_u32_e32 v15, 0x80, v14
	v_mov_b64_e32 v[4:5], s[16:17]
	v_mad_i64_i32 v[4:5], s[2:3], v15, s67, v[4:5]
	v_lshl_add_u64 v[4:5], v[2:3], 1, v[4:5]
	v_cvt_pk_bf16_f32 v6, v6, v7
	v_cvt_pk_bf16_f32 v7, v10, v11
	v_cvt_pk_bf16_f32 v8, v8, v9
	v_cvt_pk_bf16_f32 v9, v12, v13
	s_cmp_gt_i32 s28, 1
	s_mov_b64 s[2:3], -1
	global_store_dwordx4 v[4:5], v[6:9], off
	s_cbranch_scc0 .LBB0_265
	s_nop 0
	s_nop 1
	v_pk_mul_f32 v[8:9], v[74:75], s[88:89]
	v_pk_mul_f32 v[12:13], v[76:77], s[88:89]
	v_pk_mul_f32 v[6:7], v[78:79], s[88:89]
	v_pk_mul_f32 v[10:11], v[80:81], s[88:89]
	v_exp_f32_e32 v8, v8
	v_exp_f32_e32 v9, v9
	v_exp_f32_e32 v12, v12
	v_exp_f32_e32 v13, v13
	v_exp_f32_e32 v6, v6
	v_exp_f32_e32 v7, v7
	v_exp_f32_e32 v10, v10
	v_exp_f32_e32 v11, v11
	v_pk_add_f32 v[8:9], v[8:9], s[90:91]
	v_pk_add_f32 v[12:13], v[12:13], s[90:91]
	v_pk_add_f32 v[6:7], v[6:7], s[90:91]
	v_pk_add_f32 v[10:11], v[10:11], s[90:91]
	v_rcp_f32_e32 v8, v8
	v_rcp_f32_e32 v9, v9
	v_rcp_f32_e32 v12, v12
	v_rcp_f32_e32 v13, v13
	v_rcp_f32_e32 v6, v6
	v_rcp_f32_e32 v7, v7
	v_rcp_f32_e32 v10, v10
	v_rcp_f32_e32 v11, v11
	s_mov_b64 s[2:3], 0

.LBB0_270:
	v_cvt_pk_bf16_f32 v6, v6, v7
	v_cvt_pk_bf16_f32 v7, v10, v11
	v_cvt_pk_bf16_f32 v8, v8, v9
	v_cvt_pk_bf16_f32 v9, v12, v13
	s_cmp_gt_i32 s28, 1
	s_mov_b64 s[2:3], -1
	global_store_dwordx4 v[4:5], v[6:9], off offset:256
	s_cbranch_scc0 .LBB0_272
	s_nop 1
	v_pk_mul_f32 v[8:9], v[98:99], s[88:89]
	v_pk_mul_f32 v[12:13], v[100:101], s[88:89]
	v_pk_mul_f32 v[6:7], v[102:103], s[88:89]
	v_pk_mul_f32 v[10:11], v[104:105], s[88:89]
	v_exp_f32_e32 v8, v8
	v_exp_f32_e32 v9, v9
	v_exp_f32_e32 v12, v12
	v_exp_f32_e32 v13, v13
	v_exp_f32_e32 v6, v6
	v_exp_f32_e32 v7, v7
	v_exp_f32_e32 v10, v10
	v_exp_f32_e32 v11, v11
	v_pk_add_f32 v[8:9], v[8:9], s[90:91]
	v_pk_add_f32 v[12:13], v[12:13], s[90:91]
	v_pk_add_f32 v[6:7], v[6:7], s[90:91]
	v_pk_add_f32 v[10:11], v[10:11], s[90:91]
	v_rcp_f32_e32 v8, v8
	v_rcp_f32_e32 v9, v9
	v_rcp_f32_e32 v12, v12
	v_rcp_f32_e32 v13, v13
	v_rcp_f32_e32 v6, v6
	v_rcp_f32_e32 v7, v7
	v_rcp_f32_e32 v10, v10
	v_rcp_f32_e32 v11, v11
	s_mov_b64 s[2:3], 0

.LBB0_277:
	v_add_u32_e32 v15, 0x90, v14
	v_mov_b64_e32 v[4:5], s[16:17]
	v_mad_i64_i32 v[4:5], s[2:3], v15, s67, v[4:5]
	v_lshl_add_u64 v[4:5], v[2:3], 1, v[4:5]
	v_cvt_pk_bf16_f32 v6, v6, v7
	v_cvt_pk_bf16_f32 v7, v10, v11
	v_cvt_pk_bf16_f32 v8, v8, v9
	v_cvt_pk_bf16_f32 v9, v12, v13
	s_cmp_gt_i32 s28, 1
	s_mov_b64 s[2:3], -1
	global_store_dwordx4 v[4:5], v[6:9], off
	s_cbranch_scc0 .LBB0_279
	s_nop 0
	s_nop 1
	v_pk_mul_f32 v[8:9], v[66:67], s[88:89]
	v_pk_mul_f32 v[12:13], v[68:69], s[88:89]
	v_pk_mul_f32 v[6:7], v[70:71], s[88:89]
	v_pk_mul_f32 v[10:11], v[72:73], s[88:89]
	v_exp_f32_e32 v8, v8
	v_exp_f32_e32 v9, v9
	v_exp_f32_e32 v12, v12
	v_exp_f32_e32 v13, v13
	v_exp_f32_e32 v6, v6
	v_exp_f32_e32 v7, v7
	v_exp_f32_e32 v10, v10
	v_exp_f32_e32 v11, v11
	v_pk_add_f32 v[8:9], v[8:9], s[90:91]
	v_pk_add_f32 v[12:13], v[12:13], s[90:91]
	v_pk_add_f32 v[6:7], v[6:7], s[90:91]
	v_pk_add_f32 v[10:11], v[10:11], s[90:91]
	v_rcp_f32_e32 v8, v8
	v_rcp_f32_e32 v9, v9
	v_rcp_f32_e32 v12, v12
	v_rcp_f32_e32 v13, v13
	v_rcp_f32_e32 v6, v6
	v_rcp_f32_e32 v7, v7
	v_rcp_f32_e32 v10, v10
	v_rcp_f32_e32 v11, v11
	s_mov_b64 s[2:3], 0

.LBB0_284:
	v_cvt_pk_bf16_f32 v6, v6, v7
	v_cvt_pk_bf16_f32 v7, v10, v11
	v_cvt_pk_bf16_f32 v8, v8, v9
	v_cvt_pk_bf16_f32 v9, v12, v13
	s_cmp_gt_i32 s28, 1
	s_mov_b64 s[2:3], -1
	global_store_dwordx4 v[4:5], v[6:9], off offset:256
	s_cbranch_scc0 .LBB0_286
	s_nop 1
	v_pk_mul_f32 v[8:9], v[90:91], s[88:89]
	v_pk_mul_f32 v[12:13], v[92:93], s[88:89]
	v_pk_mul_f32 v[6:7], v[94:95], s[88:89]
	v_pk_mul_f32 v[10:11], v[96:97], s[88:89]
	v_exp_f32_e32 v8, v8
	v_exp_f32_e32 v9, v9
	v_exp_f32_e32 v12, v12
	v_exp_f32_e32 v13, v13
	v_exp_f32_e32 v6, v6
	v_exp_f32_e32 v7, v7
	v_exp_f32_e32 v10, v10
	v_exp_f32_e32 v11, v11
	v_pk_add_f32 v[8:9], v[8:9], s[90:91]
	v_pk_add_f32 v[12:13], v[12:13], s[90:91]
	v_pk_add_f32 v[6:7], v[6:7], s[90:91]
	v_pk_add_f32 v[10:11], v[10:11], s[90:91]
	v_rcp_f32_e32 v8, v8
	v_rcp_f32_e32 v9, v9
	v_rcp_f32_e32 v12, v12
	v_rcp_f32_e32 v13, v13
	v_rcp_f32_e32 v6, v6
	v_rcp_f32_e32 v7, v7
	v_rcp_f32_e32 v10, v10
	v_rcp_f32_e32 v11, v11
	s_mov_b64 s[2:3], 0

.LBB0_291:
	v_add_u32_e32 v15, 0xa0, v14
	v_mov_b64_e32 v[4:5], s[16:17]
	v_mad_i64_i32 v[4:5], s[2:3], v15, s67, v[4:5]
	v_lshl_add_u64 v[4:5], v[2:3], 1, v[4:5]
	v_cvt_pk_bf16_f32 v6, v6, v7
	v_cvt_pk_bf16_f32 v7, v10, v11
	v_cvt_pk_bf16_f32 v8, v8, v9
	v_cvt_pk_bf16_f32 v9, v12, v13
	s_cmp_gt_i32 s28, 1
	s_mov_b64 s[2:3], -1
	global_store_dwordx4 v[4:5], v[6:9], off
	s_cbranch_scc0 .LBB0_293
	s_nop 0
	s_nop 1
	v_pk_mul_f32 v[8:9], v[58:59], s[88:89]
	v_pk_mul_f32 v[12:13], v[60:61], s[88:89]
	v_pk_mul_f32 v[6:7], v[62:63], s[88:89]
	v_pk_mul_f32 v[10:11], v[64:65], s[88:89]
	v_exp_f32_e32 v8, v8
	v_exp_f32_e32 v9, v9
	v_exp_f32_e32 v12, v12
	v_exp_f32_e32 v13, v13
	v_exp_f32_e32 v6, v6
	v_exp_f32_e32 v7, v7
	v_exp_f32_e32 v10, v10
	v_exp_f32_e32 v11, v11
	v_pk_add_f32 v[8:9], v[8:9], s[90:91]
	v_pk_add_f32 v[12:13], v[12:13], s[90:91]
	v_pk_add_f32 v[6:7], v[6:7], s[90:91]
	v_pk_add_f32 v[10:11], v[10:11], s[90:91]
	v_rcp_f32_e32 v8, v8
	v_rcp_f32_e32 v9, v9
	v_rcp_f32_e32 v12, v12
	v_rcp_f32_e32 v13, v13
	v_rcp_f32_e32 v6, v6
	v_rcp_f32_e32 v7, v7
	v_rcp_f32_e32 v10, v10
	v_rcp_f32_e32 v11, v11
	s_mov_b64 s[2:3], 0

.LBB0_298:
	v_cvt_pk_bf16_f32 v6, v6, v7
	v_cvt_pk_bf16_f32 v7, v10, v11
	v_cvt_pk_bf16_f32 v8, v8, v9
	v_cvt_pk_bf16_f32 v9, v12, v13
	s_cmp_gt_i32 s28, 1
	s_mov_b64 s[2:3], -1
	global_store_dwordx4 v[4:5], v[6:9], off offset:256
	s_cbranch_scc0 .LBB0_300
	s_nop 1
	v_pk_mul_f32 v[6:7], v[82:83], s[88:89]
	v_pk_mul_f32 v[10:11], v[84:85], s[88:89]
	v_pk_mul_f32 v[4:5], v[86:87], s[88:89]
	v_pk_mul_f32 v[8:9], v[88:89], s[88:89]
	v_exp_f32_e32 v6, v6
	v_exp_f32_e32 v7, v7
	v_exp_f32_e32 v10, v10
	v_exp_f32_e32 v11, v11
	v_exp_f32_e32 v4, v4
	v_exp_f32_e32 v5, v5
	v_exp_f32_e32 v8, v8
	v_exp_f32_e32 v9, v9
	v_pk_add_f32 v[6:7], v[6:7], s[90:91]
	v_pk_add_f32 v[10:11], v[10:11], s[90:91]
	v_pk_add_f32 v[4:5], v[4:5], s[90:91]
	v_pk_add_f32 v[8:9], v[8:9], s[90:91]
	v_rcp_f32_e32 v6, v6
	v_rcp_f32_e32 v7, v7
	v_rcp_f32_e32 v10, v10
	v_rcp_f32_e32 v11, v11
	v_rcp_f32_e32 v4, v4
	v_rcp_f32_e32 v5, v5
	v_rcp_f32_e32 v8, v8
	v_rcp_f32_e32 v9, v9
	s_mov_b64 s[2:3], 0

.LBB0_305:
	v_add_u32_e32 v14, 0xb0, v14
	v_mov_b64_e32 v[12:13], s[16:17]
	v_mad_i64_i32 v[12:13], s[2:3], v14, s67, v[12:13]
	v_lshl_add_u64 v[2:3], v[2:3], 1, v[12:13]
	v_cvt_pk_bf16_f32 v4, v4, v5
	v_cvt_pk_bf16_f32 v5, v8, v9
	v_cvt_pk_bf16_f32 v6, v6, v7
	v_cvt_pk_bf16_f32 v7, v10, v11
	s_cmp_gt_i32 s28, 1
	s_mov_b64 s[2:3], -1
	global_store_dwordx4 v[2:3], v[4:7], off
	s_cbranch_scc0 .LBB0_307
	s_nop 0
	s_nop 1
	v_pk_mul_f32 v[6:7], v[50:51], s[88:89]
	v_pk_mul_f32 v[10:11], v[52:53], s[88:89]
	v_pk_mul_f32 v[4:5], v[54:55], s[88:89]
	v_pk_mul_f32 v[8:9], v[56:57], s[88:89]
	v_exp_f32_e32 v6, v6
	v_exp_f32_e32 v7, v7
	v_exp_f32_e32 v10, v10
	v_exp_f32_e32 v11, v11
	v_exp_f32_e32 v4, v4
	v_exp_f32_e32 v5, v5
	v_exp_f32_e32 v8, v8
	v_exp_f32_e32 v9, v9
	v_pk_add_f32 v[6:7], v[6:7], s[90:91]
	v_pk_add_f32 v[10:11], v[10:11], s[90:91]
	v_pk_add_f32 v[4:5], v[4:5], s[90:91]
	v_pk_add_f32 v[8:9], v[8:9], s[90:91]
	v_rcp_f32_e32 v6, v6
	v_rcp_f32_e32 v7, v7
	v_rcp_f32_e32 v10, v10
	v_rcp_f32_e32 v11, v11
	v_rcp_f32_e32 v4, v4
	v_rcp_f32_e32 v5, v5
	v_rcp_f32_e32 v8, v8
	v_rcp_f32_e32 v9, v9
	s_mov_b64 s[2:3], 0

.LBB0_965:
	v_and_b32_e32 v3, 48, v0
	v_lshrrev_b32_e32 v2, 4, v178
	v_lshl_or_b32 v3, v199, 6, v3
	v_lshlrev_b32_e32 v4, 3, v199
	s_lshl_b32 s2, s14, 12
	v_lshl_or_b32 v4, v2, 7, v4
	v_bitop3_b32 v5, s2, v3, v1 bitop3:0xf6
	s_lshl_b32 s2, s13, 11
	v_bitop3_b32 v200, s2, v3, v1 bitop3:0xf6
	v_or_b32_e32 v3, s12, v4
	s_lshl_b32 s2, s13, 5
	s_waitcnt vmcnt(4)
	v_or_b32_e32 v201, 0x2000, v3
	v_lshl_or_b32 v3, s14, 11, v4
	s_add_i32 s43, s12, 0
	v_lshl_or_b32 v2, v2, 3, s2
	v_mov_b32_e32 v50, 0
	s_mov_b32 s70, 0
	s_add_i32 s44, s43, 0xe000
	s_add_i32 s45, s43, 0x10000
	s_add_i32 s46, s43, 0x12000
	s_add_i32 s47, s43, 0x14000
	s_add_i32 s48, s43, 0x16000
	s_add_i32 s49, s43, 0x2000
	s_add_i32 s50, s43, 0x6000
	s_add_i32 s51, s43, 0x18000
	s_add_i32 s52, s43, 0x1a000
	s_add_i32 s53, s43, 0x1c000
	s_add_i32 s54, s43, 0x1e000
	s_add_i32 s55, s43, 0xa000
	v_lshl_or_b32 v202, s14, 6, v199
	s_add_i32 s56, s43, 0xd000
	s_add_i32 s57, s43, 0x11000
	s_add_i32 s58, s43, 0x15000
	s_add_i32 s59, s43, 0x1000
	s_add_i32 s60, s43, 0x5000
	s_add_i32 s61, s43, 0x19000
	s_add_i32 s62, s43, 0x1d000
	s_add_i32 s63, s43, 0x9000
	v_or_b32_e32 v203, 0x1400, v2
	v_mov_b64_e32 v[186:187], 0xa20
	v_mov_b64_e32 v[188:189], 0xa1f
	s_add_i32 s64, s43, 0xc000
	v_mov_b32_e32 v204, 0x7f7f7f7f
	s_add_i32 s65, s43, 0x4000
	s_add_i32 s66, s43, 0x8000
	s_mov_b32 s24, 0x3b800000
	s_mov_b32 s67, 0xcc00
	v_add_u32_e32 v205, 0, v5
	v_add_u32_e32 v206, 0, v3
	v_mov_b32_e32 v51, v50
	v_mov_b32_e32 v52, v50
	v_mov_b32_e32 v53, v50
	v_mov_b32_e32 v54, v50
	v_mov_b32_e32 v55, v50
	v_mov_b32_e32 v56, v50
	v_mov_b32_e32 v57, v50
	v_mov_b32_e32 v58, v50
	v_mov_b32_e32 v59, v50
	v_mov_b32_e32 v60, v50
	v_mov_b32_e32 v61, v50
	v_mov_b32_e32 v62, v50
	v_mov_b32_e32 v63, v50
	v_mov_b32_e32 v64, v50
	v_mov_b32_e32 v65, v50
	v_mov_b32_e32 v66, v50
	v_mov_b32_e32 v67, v50
	v_mov_b32_e32 v68, v50
	v_mov_b32_e32 v69, v50
	v_mov_b32_e32 v70, v50
	v_mov_b32_e32 v71, v50
	v_mov_b32_e32 v72, v50
	v_mov_b32_e32 v73, v50
	v_mov_b32_e32 v74, v50
	v_mov_b32_e32 v75, v50
	v_mov_b32_e32 v76, v50
	v_mov_b32_e32 v77, v50
	v_mov_b32_e32 v78, v50
	v_mov_b32_e32 v79, v50
	v_mov_b32_e32 v80, v50
	v_mov_b32_e32 v81, v50
	v_mov_b32_e32 v82, v50
	v_mov_b32_e32 v83, v50
	v_mov_b32_e32 v84, v50
	v_mov_b32_e32 v85, v50
	v_mov_b32_e32 v86, v50
	v_mov_b32_e32 v87, v50
	v_mov_b32_e32 v88, v50
	v_mov_b32_e32 v89, v50
	v_mov_b32_e32 v90, v50
	v_mov_b32_e32 v91, v50
	v_mov_b32_e32 v92, v50
	v_mov_b32_e32 v93, v50
	v_mov_b32_e32 v94, v50
	v_mov_b32_e32 v95, v50
	v_mov_b32_e32 v96, v50
	v_mov_b32_e32 v97, v50
	v_mov_b32_e32 v98, v50
	v_mov_b32_e32 v99, v50
	v_mov_b32_e32 v100, v50
	v_mov_b32_e32 v101, v50
	v_mov_b32_e32 v102, v50
	v_mov_b32_e32 v103, v50
	v_mov_b32_e32 v104, v50
	v_mov_b32_e32 v105, v50
	v_mov_b32_e32 v106, v50
	v_mov_b32_e32 v107, v50
	v_mov_b32_e32 v108, v50
	v_mov_b32_e32 v109, v50
	v_mov_b32_e32 v110, v50
	v_mov_b32_e32 v111, v50
	v_mov_b32_e32 v112, v50
	v_mov_b32_e32 v113, v50
	v_mov_b32_e32 v114, v50
	v_mov_b32_e32 v115, v50
	v_mov_b32_e32 v116, v50
	v_mov_b32_e32 v117, v50
	v_mov_b32_e32 v118, v50
	v_mov_b32_e32 v119, v50
	v_mov_b32_e32 v120, v50
	v_mov_b32_e32 v121, v50
	v_mov_b32_e32 v122, v50
	v_mov_b32_e32 v123, v50
	v_mov_b32_e32 v124, v50
	v_mov_b32_e32 v125, v50
	v_mov_b32_e32 v126, v50
	v_mov_b32_e32 v127, v50
	v_mov_b32_e32 v128, v50
	v_mov_b32_e32 v129, v50
	v_mov_b32_e32 v130, v50
	v_mov_b32_e32 v131, v50
	v_mov_b32_e32 v132, v50
	v_mov_b32_e32 v133, v50
	v_mov_b32_e32 v134, v50
	v_mov_b32_e32 v135, v50
	v_mov_b32_e32 v136, v50
	v_mov_b32_e32 v137, v50
	v_mov_b32_e32 v138, v50
	v_mov_b32_e32 v139, v50
	v_mov_b32_e32 v140, v50
	v_mov_b32_e32 v141, v50
	v_mov_b32_e32 v142, v50
	v_mov_b32_e32 v143, v50
	v_mov_b32_e32 v144, v50
	v_mov_b32_e32 v145, v50
	v_mov_b32_e32 v146, v50
	v_mov_b32_e32 v147, v50
	v_mov_b32_e32 v148, v50
	v_mov_b32_e32 v149, v50
	v_mov_b32_e32 v150, v50
	v_mov_b32_e32 v151, v50
	v_mov_b32_e32 v152, v50
	v_mov_b32_e32 v153, v50
	v_mov_b32_e32 v154, v50
	v_mov_b32_e32 v155, v50
	v_mov_b32_e32 v156, v50
	v_mov_b32_e32 v157, v50
	v_mov_b32_e32 v158, v50
	v_mov_b32_e32 v159, v50
	v_mov_b32_e32 v160, v50
	v_mov_b32_e32 v161, v50
	v_mov_b32_e32 v162, v50
	v_mov_b32_e32 v163, v50
	v_mov_b32_e32 v164, v50
	v_mov_b32_e32 v165, v50
	v_mov_b32_e32 v166, v50
	v_mov_b32_e32 v167, v50
	v_mov_b32_e32 v168, v50
	v_mov_b32_e32 v169, v50
	v_mov_b32_e32 v170, v50
	v_mov_b32_e32 v171, v50
	v_mov_b32_e32 v172, v50
	v_mov_b32_e32 v173, v50
	v_mov_b32_e32 v174, v50
	v_mov_b32_e32 v175, v50
	v_mov_b32_e32 v176, v50
	v_mov_b32_e32 v177, v50
	s_barrier
	s_mov_b32 s32, 1
	s_mov_b32 s84, 0
	v_mov_b32_e32 v244, v180
	v_mov_b32_e32 v245, v182
	v_mov_b32_e32 v246, v184
	s_mov_b32 s88, 0xbbb8aa3b
	s_mov_b32 s89, 0xbbb8aa3b
	s_mov_b32 s90, 1.0
	s_mov_b32 s91, 1.0
	s_branch .LBB0_968

.LBB0_1001:
	v_lshl_add_u32 v14, s38, 8, v202
	v_lshl_add_u32 v2, s37, 8, v203
	v_mov_b64_e32 v[4:5], s[16:17]
	v_ashrrev_i32_e32 v3, 31, v2
	v_mad_i64_i32 v[4:5], s[2:3], v14, s67, v[4:5]
	v_lshl_add_u64 v[4:5], v[2:3], 1, v[4:5]
	v_cvt_pk_bf16_f32 v6, v6, v7
	v_cvt_pk_bf16_f32 v7, v10, v11
	v_cvt_pk_bf16_f32 v8, v8, v9
	v_cvt_pk_bf16_f32 v9, v12, v13
	s_cmp_gt_i32 s28, 1
	s_mov_b64 s[2:3], -1
	global_store_dwordx4 v[4:5], v[6:9], off
	s_cbranch_scc0 .LBB0_1003
	s_nop 0
	s_nop 1
	v_pk_mul_f32 v[8:9], v[138:139], s[88:89]
	v_pk_mul_f32 v[12:13], v[140:141], s[88:89]
	v_pk_mul_f32 v[6:7], v[142:143], s[88:89]
	v_pk_mul_f32 v[10:11], v[144:145], s[88:89]
	v_exp_f32_e32 v8, v8
	v_exp_f32_e32 v9, v9
	v_exp_f32_e32 v12, v12
	v_exp_f32_e32 v13, v13
	v_exp_f32_e32 v6, v6
	v_exp_f32_e32 v7, v7
	v_exp_f32_e32 v10, v10
	v_exp_f32_e32 v11, v11
	v_pk_add_f32 v[8:9], v[8:9], s[90:91]
	v_pk_add_f32 v[12:13], v[12:13], s[90:91]
	v_pk_add_f32 v[6:7], v[6:7], s[90:91]
	v_pk_add_f32 v[10:11], v[10:11], s[90:91]
	v_rcp_f32_e32 v8, v8
	v_rcp_f32_e32 v9, v9
	v_rcp_f32_e32 v12, v12
	v_rcp_f32_e32 v13, v13
	v_rcp_f32_e32 v6, v6
	v_rcp_f32_e32 v7, v7
	v_rcp_f32_e32 v10, v10
	v_rcp_f32_e32 v11, v11
	s_mov_b64 s[2:3], 0
